# v40
# baseline (speedup 1.0000x reference)
; #define WS_(p) opq_ws((p).ws)
; DI void mla_item(const Params& p, int b, int h, int qb) {
;     ...
;   const int tid = tid_o, w = tid >> 6, lane = tid & 63, r = lane & 31, hh = lane >> 5;
;   unsigned* ctr = (unsigned*)(WS_(p) + OFF_CTR) + L * 32 + rep * 16;
;   unsigned* bc = (unsigned*)(smem + SHM_BYTES - 16);
;   const int qlen[8] = {132, 132, 132, 132, 132, 132, 132, 132};
;   for (;;) {
;     const int it = next_item(ctr, qlen, bc);
.LBB0_859:
	s_or_b64 exec, exec, s[36:37]
	s_lshl_b32 s50, s50, 5
	s_mov_b64 s[4:5], s[70:71]
	s_waitcnt lgkmcnt(0)
	s_barrier
	s_lshl_b64 s[0:1], s[50:51], 2
	s_add_u32 s4, s4, s0
	s_addc_u32 s5, s5, s1
	s_add_u32 s26, s4, 0x404000
	s_addc_u32 s27, s5, 0
	v_readlane_b32 s50, v254, 47
	v_readfirstlane_b32 s100, v178
	s_nop 3
	s_lshr_b32 s100, s100, 6
	s_cmp_lt_u32 s100, 4
	s_cbranch_scc0 .Lprio_skip
	s_setprio 2
